# addon_latewt_xcc
# speedup vs baseline: 1.0183x; 1.0002x over previous
; #define LAS __attribute__((address_space(3)))
; __device__ __forceinline__ void p0_prologue(const Args& a, LAS unsigned char* lds, int wave, int lane) {
;     if (wave < 6) {
;         LAS float* scr = (LAS float*)(lds + wave * 16384);
;         const int gw = blockIdx.x * 6 + wave, NGW = gridDim.x * 6;
;         const float* w_in = a.in[3]; const float* w_oa = a.in[10]; const float* w_ob = a.in[11]; const float* w_o = a.in[12]; const float* ng = a.in[2];
;         bf16_t* WIN = (bf16_t*)(a.ws + WS_WIN); bf16_t* WAB = (bf16_t*)(a.ws + WS_WAB); bf16_t* WO = (bf16_t*)(a.ws + WS_WO);
;         constexpr int I_IN = 16 * 168, I_OA = 8 * 32, I_OB = 8 * 32, I_O = 16 * 32, NITEMS = I_IN + I_OA + I_OB + I_O;
;         for (int it = gw; it < NITEMS; it += NGW) {
;             int r = it;
;             if (r < I_IN) { const int kb = r / 168, nb = r % 168; p0_transpose_item(w_in, NIN, 64 * kb, map_col(32 * nb), ng, WIN, 32 * nb, 64 * kb, scr, lane); continue; } r -= I_IN;
;             if (r < I_OA) { const int kb = r / 32, nb = r % 32; p0_transpose_item(w_oa, 1024, 64 * kb, 32 * nb, nullptr, WAB, 32 * nb, 64 * kb, scr, lane); continue; } r -= I_OA;
;             if (r < I_OB) { const int kb = r / 32, nb = r % 32; p0_transpose_item(w_ob, 1024, 64 * kb, 32 * nb, nullptr, WAB, 32 * nb, 512 + 64 * kb, scr, lane); continue; } r -= I_OB;
;             { const int kb = r / 32, nb = r % 32; p0_transpose_item(w_o, 1024, 64 * kb, 32 * nb, nullptr, WO, 32 * nb, 64 * kb, scr, lane); }
;         }
;     } else {
;         bf16_t* XB = (bf16_t*)(a.ws + WS_XB);
;         const int gw = blockIdx.x * 2 + (wave - 6), NGW = gridDim.x * 2;
; __global__ void __launch_bounds__(512, 2) fwd_kernel(Args a) {
;     ...
;     const int tid = threadIdx.x, lane = tid & 63, wave = __builtin_amdgcn_readfirstlane(tid >> 6);
;     const int lo = a.ph_lo, hi = a.ph_hi;
;     unsigned char* ws = a.ws;
;     ...
;     volatile LAS unsigned* bst = (volatile LAS unsigned*)(lds + LDS_BYTES - 64);
;     if (tid == 0) { bst[0] = 0u; bst[1] = 0u; }
;     __syncthreads();
;     (void)xcd_barrier_post((unsigned*)(ws + WS_CTL), bst);
;     if (lo == 12345) cg::this_grid().sync();
;     ...
;     if (IN(0)) { p0_prologue(a, lds, wave, lane); }
.LBB0_17:
	s_cmp_lt_u32 s48, 64
	s_cbranch_scc0 .Lxcc_noor
	s_getreg_b32 s100, hwreg(HW_REG_XCC_ID, 0, 4)
	s_lshl_b32 s100, 1, s100
	v_mov_b32_e32 v255, s100
	s_and_b32 s100, s2, 7
	s_lshl_b32 s100, s100, 7
	s_add_u32 s100, s100, s92
	s_addc_u32 s101, s93, 0
	s_add_u32 s100, s100, 0x3c00
	s_addc_u32 s101, s101, 0
	v_mov_b32_e32 v254, 0
	s_mov_b64 exec, 1
	global_atomic_or v254, v255, s[100:101]
	s_mov_b64 exec, -1
.Lxcc_noor:
	s_movk_i32 s32, 0xa7f
	s_lshr_b32 s3, s48, 6
	s_cmp_lt_i32 s66, 1
	s_cselect_b64 s[0:1], -1, 0
	s_cmp_gt_i32 s67, 0
	s_cselect_b64 s[4:5], -1, 0
	s_and_b64 s[4:5], s[0:1], s[4:5]
	s_andn2_b64 vcc, exec, s[4:5]
	v_and_b32_e32 v191, 63, v190
	s_cbranch_vccnz .LBB0_106
	s_cmpk_gt_u32 s48, 0x17f
	s_mov_b64 s[0:1], -1
	s_cbranch_scc0 .LBB0_41
	s_load_dword s6, s[74:75], 0x80
	s_lshl_b32 s12, s2, 1
	s_add_i32 s10, s12, s3
	s_add_i32 s10, s10, -6
	s_cmp_lt_i32 s10, 0x4000
	s_waitcnt lgkmcnt(0)
	s_mul_i32 s8, s6, 6
	s_cbranch_scc1 .LBB0_21
	s_lshl_b32 s7, s6, 2
	s_mul_i32 s9, s6, 6
	s_mov_b64 s[0:1], 0
	s_andn2_b64 vcc, exec, s[0:1]
	v_lshlrev_b32_e32 v130, 4, v191
	s_cbranch_vccnz .LBB0_23
	s_branch .LBB0_22

; #define LAS __attribute__((address_space(3)))
; __device__ __forceinline__ void p0_transpose_item(const float* W, int N, int ksrc0, int nsrc0, const float* ksc, bf16_t* WT, int nrow0, int kdst0, LAS float* scr, int lane) {
; #pragma unroll 8
;     for (int i = 0; i < 32; ++i) { const int kk = 2 * i + (lane >> 5); float v = W[(size_t)(ksrc0 + kk) * N + nsrc0 + (lane & 31)]; if (ksc) v *= ksc[ksrc0 + kk]; scr[kk * 33 + (lane & 31)] = v; }
; __device__ __forceinline__ void p0_prologue(const Args& a, LAS unsigned char* lds, int wave, int lane) {
;     if (wave < 6) {
;         LAS float* scr = (LAS float*)(lds + wave * 16384);
;         const int gw = blockIdx.x * 6 + wave, NGW = gridDim.x * 6;
;         const float* w_in = a.in[3]; const float* w_oa = a.in[10]; const float* w_ob = a.in[11]; const float* w_o = a.in[12]; const float* ng = a.in[2];
;         bf16_t* WIN = (bf16_t*)(a.ws + WS_WIN); bf16_t* WAB = (bf16_t*)(a.ws + WS_WAB); bf16_t* WO = (bf16_t*)(a.ws + WS_WO);
;         constexpr int I_IN = 16 * 168, I_OA = 8 * 32, I_OB = 8 * 32, I_O = 16 * 32, NITEMS = I_IN + I_OA + I_OB + I_O;
;         for (int it = gw; it < NITEMS; it += NGW) {
;             int r = it;
;             if (r < I_IN) { const int kb = r / 168, nb = r % 168; p0_transpose_item(w_in, NIN, 64 * kb, map_col(32 * nb), ng, WIN, 32 * nb, 64 * kb, scr, lane); continue; } r -= I_IN;
.LBB0_41:
	s_and_b64 vcc, exec, s[0:1]
	s_cbranch_vccz .LBB0_106
	s_mul_i32 s0, s2, 6
	s_add_i32 s20, s3, s0
	s_cmp_gt_i32 s20, s32
	s_cbranch_scc1 .Lp0t_exit
.Llate_entry:
	s_load_dword s21, s[74:75], 0x80
	s_waitcnt vmcnt(15)
	v_and_b32_e32 v1, 31, v190
	s_load_dwordx8 s[12:19], s[74:75], 0x40
	s_add_u32 s6, s64, 0xb00000
	v_lshlrev_b32_e32 v2, 2, v1
	v_lshlrev_b32_e32 v1, 3, v190
	s_addc_u32 s7, s65, 0
	s_lshl_b32 s8, s3, 14
	v_lshrrev_b32_e32 v0, 5, v191
	v_mov_b32_e32 v3, 0
	s_waitcnt vmcnt(10)
	v_and_b32_e32 v20, 56, v1
	s_add_i32 s10, s8, 0
	v_lshrrev_b32_e32 v7, 3, v191
	v_lshlrev_b32_e32 v16, 1, v20
	v_mov_b32_e32 v17, v3
	v_mul_u32_u24_e32 v18, 0x84, v0
	v_mul_u32_u24_e32 v1, 0x84, v20
	v_lshl_add_u64 v[8:9], s[64:65], 0, v[16:17]
	s_mov_b64 s[0:1], 0xd00000
	v_lshlrev_b32_e32 v12, 2, v7
	s_waitcnt lgkmcnt(0)
	s_cmp_lg_u64 s[80:81], 0
	v_or_b32_e32 v18, s8, v18
	s_movk_i32 s12, 0xd600
	s_mov_b32 s9, 0
	s_mul_i32 s21, s21, 6
	v_lshl_add_u64 v[4:5], s[60:61], 0, v[2:3]
	v_add_u32_e32 v6, s10, v2
	s_movk_i32 s22, 0x84
	v_lshl_add_u64 v[10:11], v[8:9], 0, s[0:1]
	s_waitcnt vmcnt(4)
	v_add3_u32 v44, s10, v1, v12
	v_or_b32_e32 v45, 8, v7
	v_or_b32_e32 v46, 16, v7
	v_or_b32_e32 v47, 24, v7
	v_lshl_add_u64 v[12:13], s[18:19], 0, v[2:3]
	v_lshl_add_u64 v[14:15], s[16:17], 0, v[2:3]
	v_lshl_add_u64 v[16:17], s[6:7], 0, v[16:17]
	s_cselect_b64 s[10:11], -1, 0
	v_mov_b32_e32 v1, v0
	s_waitcnt vmcnt(3)
	v_add3_u32 v48, v18, v2, 0
	v_lshl_add_u64 v[18:19], s[82:83], 0, v[2:3]
	v_or_b32_e32 v49, 14, v0
	v_or_b32_e32 v50, 12, v0
	v_or_b32_e32 v51, 10, v0
	s_waitcnt vmcnt(2)
	v_or_b32_e32 v52, 8, v0
	v_or_b32_e32 v53, 6, v0
	v_or_b32_e32 v54, 4, v0
	v_or_b32_e32 v55, 2, v0
	v_lshlrev_b32_e32 v20, 1, v20
	s_mov_b32 s13, -1
	s_movk_i32 s23, 0xd00
	s_movk_i32 s24, 0x5400
	s_cmpk_eq_u32 s32, 0xe7f
	s_cselect_b32 s21, 0x200, s21
	s_branch .LBB0_46

; __device__ __forceinline__ void p0_prologue(const Args& a, LAS unsigned char* lds, int wave, int lane) {
;     ...
;         for (int it = gw; it < NITEMS; it += NGW) {
;             int r = it;
;             if (r < I_IN) { const int kb = r / 168, nb = r % 168; p0_transpose_item(w_in, NIN, 64 * kb, map_col(32 * nb), ng, WIN, 32 * nb, 64 * kb, scr, lane); continue; } r -= I_IN;
.LBB0_45:
	s_add_i32 s20, s20, s21
	s_cmp_gt_i32 s20, s32
	s_cbranch_scc1 .Lp0t_exit

; __device__ __forceinline__ void p0_prologue(const Args& a, LAS unsigned char* lds, int wave, int lane) {
;     ...
;         for (int it = gw; it < NITEMS; it += NGW) {
;             int r = it;
;             if (r < I_IN) { const int kb = r / 168, nb = r % 168; p0_transpose_item(w_in, NIN, 64 * kb, map_col(32 * nb), ng, WIN, 32 * nb, 64 * kb, scr, lane); continue; } r -= I_IN;
;             if (r < I_OA) { const int kb = r / 32, nb = r % 32; p0_transpose_item(w_oa, 1024, 64 * kb, 32 * nb, nullptr, WAB, 32 * nb, 64 * kb, scr, lane); continue; } r -= I_OA;
;             if (r < I_OB) { const int kb = r / 32, nb = r % 32; p0_transpose_item(w_ob, 1024, 64 * kb, 32 * nb, nullptr, WAB, 32 * nb, 512 + 64 * kb, scr, lane); continue; } r -= I_OB;
;             { const int kb = r / 32, nb = r % 32; p0_transpose_item(w_o, 1024, 64 * kb, 32 * nb, nullptr, WO, 32 * nb, 64 * kb, scr, lane); }
;         }
.Lp0t_exit:
	s_cmpk_eq_u32 s32, 0xe7f
	s_cbranch_scc1 .Llate_done

;     __device__ bool next(int i, Unit& u) const {
;         const long L = (long)i * G + c; if (L >= nwg) return false;
;         int wgid = (int)L; { const int q = nwg / NXCD, r = nwg % NXCD, xcd = wgid % NXCD, off = wgid / NXCD; wgid = (xcd < r ? xcd * (q + 1) : r * (q + 1) + (xcd - r) * q) + off; }
;         const int nig = WGM * nN, gid = wgid / nig, fm = gid * WGM, gsz = (nM - fm) < WGM ? (nM - fm) : WGM;
;         u.pm = fm + ((wgid % nig) % gsz); u.pn = (wgid % nig) / gsz; return true;
; __global__ void __launch_bounds__(512, 2) fwd_kernel(Args a) {
;     ...
;     if (IN(1)) {
;         SchedA S; S.init(T, NIN, gridDim.x, blockIdx.x); S.XB = (const char*)(ws + WS_XB); S.W = (const char*)(ws + WS_WIN);
;         EpiA E; E.ws = ws; E.GA = (bf16_t*)a.out;
;         E.qn_a = a.in[4]; E.kn_a = a.in[5]; E.qn_b = a.in[7]; E.kn_b = a.in[8];
;         pg8::gemm_phase<EpiA, SchedA>(lds, S, E);
.LBB0_160:
	s_cmp_lt_i32 s66, 2
	s_cselect_b64 s[4:5], -1, 0
	s_and_b64 s[6:7], s[4:5], s[0:1]
	s_andn2_b64 vcc, exec, s[6:7]
	s_cbranch_vccnz .LBB0_212
	s_and_b32 s100, s2, 7
	s_lshl_b32 s100, s100, 7
	s_add_u32 s100, s100, s92
	s_addc_u32 s101, s93, 0
	s_add_u32 s100, s100, 0x3c00
	s_addc_u32 s101, s101, 0
	v_mov_b32_e32 v254, 0
	global_load_dword v255, v254, s[100:101] sc1
	s_waitcnt vmcnt(0)
	v_readfirstlane_b32 s32, v255
	s_nop 0
	s_bcnt1_i32_b32 s32, s32
	s_mov_b32 s99, -1
	s_cmpk_lt_i32 s2, 0xfc0
	s_cselect_b64 s[0:1], -1, 0
	s_cmpk_gt_i32 s2, 0xfbf
	v_readfirstlane_b32 s4, v190
	s_cbranch_scc1 .LBB0_163
	s_ashr_i32 s5, s2, 31
	s_lshr_b32 s5, s5, 29
	s_add_i32 s5, s2, s5
	s_ashr_i32 s8, s5, 3
	s_and_b32 s5, s5, -8
	s_sub_i32 s5, s2, s5
	s_cmp_lt_i32 s5, 0
	s_movk_i32 s9, 0x1f9
	s_cselect_b32 s9, s9, 0x1f8
	s_mul_i32 s5, s5, s9
	s_add_i32 s5, s5, s8
	s_mul_hi_i32 s8, s5, 0x30c30c31
	s_lshr_b32 s9, s8, 31
	s_ashr_i32 s8, s8, 4
	s_add_i32 s8, s8, s9
	s_lshl_b32 s9, s8, 2
	s_mulk_i32 s8, 0x54
	s_sub_i32 s5, s5, s8
	s_bfe_i32 s8, s5, 0x80000
	s_bfe_u32 s8, s8, 0x2000d
	s_add_i32 s8, s5, s8
	s_bfe_i32 s10, s8, 0x80000
	s_and_b32 s8, s8, 0xfc
	s_sub_i32 s5, s5, s8
	s_sext_i32_i16 s10, s10
	s_sext_i32_i8 s5, s5
	s_add_i32 s8, s9, s5
	s_ashr_i32 s38, s10, 2
	s_mul_i32 s100, s8, 0xaab
	s_lshr_b32 s100, s100, 16
	s_mul_i32 s101, s100, 24
	s_sub_i32 s101, s8, s101
	s_lshl_b32 s101, s101, 3
	s_or_b32 s8, s101, s100

; __device__ __forceinline__ unsigned cvt_pk_bf16(float lo, float hi) { const f32x2_t v = {lo, hi}; const bf16x2_t r = __builtin_convertvector(v, bf16x2_t); return __builtin_bit_cast(unsigned, r); }
; __device__ __forceinline__ void p0_proc4(bf16_t* XB, int m0, int NGW, int lane, const f32x4 (&v)[4][4]) {
;     float s[4];
; #pragma unroll
;     for (int u = 0; u < 4; ++u) { float t = 0.f;
; #pragma unroll
;         for (int j = 0; j < 4; ++j) t += (v[u][j][0] * v[u][j][0] + v[u][j][1] * v[u][j][1]) + (v[u][j][2] * v[u][j][2] + v[u][j][3] * v[u][j][3]);
;         s[u] = t; }
; #pragma unroll
;     for (int o = 1; o < 64; o <<= 1) {
; #pragma unroll
;         for (int u = 0; u < 4; ++u) s[u] += __shfl_xor(s[u], o); }
; #pragma unroll
;     for (int u = 0; u < 4; ++u) { const int m = m0 + u * NGW; if (m >= T) break;
;         const float rstd = 1.0f / sqrtf(s[u] * (1.0f / 1024.0f) + NORM_EPS);
;         u32x2* o8 = (u32x2*)(XB + (size_t)m * 1024) + lane;
; #pragma unroll
;         for (int j = 0; j < 4; ++j) { u32x2 w; w.x = cvt_pk_bf16(v[u][j][0] * rstd, v[u][j][1] * rstd); w.y = cvt_pk_bf16(v[u][j][2] * rstd, v[u][j][3] * rstd); o8[64 * j] = w; } }
.LBB0_208:
	s_cmp_eq_u32 s98, -1
	s_cbranch_scc1 .Lax_done
	s_waitcnt vmcnt(16)
	v_mul_f32_e32 v203, v232, v232
	v_mul_f32_e32 v204, v234, v234
	v_fmac_f32_e32 v203, v233, v233
	v_fmac_f32_e32 v204, v235, v235
	v_add_f32_e32 v203, v203, v204
	v_mov_b32_e32 v201, v203
	v_mul_f32_e32 v203, v236, v236
	v_mul_f32_e32 v204, v238, v238
	v_fmac_f32_e32 v203, v237, v237
	v_fmac_f32_e32 v204, v239, v239
	v_add_f32_e32 v203, v203, v204
	v_add_f32_e32 v201, v201, v203
	v_mul_f32_e32 v203, v240, v240
	v_mul_f32_e32 v204, v242, v242
	v_fmac_f32_e32 v203, v241, v241
	v_fmac_f32_e32 v204, v243, v243
	v_add_f32_e32 v203, v203, v204
	v_add_f32_e32 v201, v201, v203
	v_mul_f32_e32 v203, v244, v244
	v_mul_f32_e32 v204, v246, v246
	v_fmac_f32_e32 v203, v245, v245
	v_fmac_f32_e32 v204, v247, v247
	v_add_f32_e32 v203, v203, v204
	v_add_f32_e32 v201, v201, v203
	v_mul_f32_e32 v205, v182, v182
	v_mul_f32_e32 v206, v184, v184
	v_fmac_f32_e32 v205, v183, v183
	v_fmac_f32_e32 v206, v185, v185
	v_add_f32_e32 v205, v205, v206
	v_mov_b32_e32 v202, v205
	v_mul_f32_e32 v205, v250, v250
	v_mul_f32_e32 v206, v252, v252
	v_fmac_f32_e32 v205, v251, v251
	v_fmac_f32_e32 v206, v253, v253
	v_add_f32_e32 v205, v205, v206
	v_add_f32_e32 v202, v202, v205
	v_mul_f32_e32 v205, v178, v178
	v_mul_f32_e32 v206, v180, v180
	v_fmac_f32_e32 v205, v179, v179
	v_fmac_f32_e32 v206, v181, v181
	v_add_f32_e32 v205, v205, v206
	v_add_f32_e32 v202, v202, v205
	v_mul_f32_e32 v205, v154, v154
	v_mul_f32_e32 v206, v156, v156
	v_fmac_f32_e32 v205, v155, v155
	v_fmac_f32_e32 v206, v157, v157
	v_add_f32_e32 v205, v205, v206
	v_add_f32_e32 v202, v202, v205
	v_lshrrev_b32_e32 v210, 2, v254
	v_xor_b32_e32 v211, 4, v210
	ds_bpermute_b32 v207, v211, v201
	ds_bpermute_b32 v208, v211, v202
	s_waitcnt lgkmcnt(0)
	v_add_f32_e32 v201, v201, v207
	v_add_f32_e32 v202, v202, v208
	v_xor_b32_e32 v211, 8, v210
	ds_bpermute_b32 v207, v211, v201
	ds_bpermute_b32 v208, v211, v202
	s_waitcnt lgkmcnt(0)
	v_add_f32_e32 v201, v201, v207
	v_add_f32_e32 v202, v202, v208
	v_xor_b32_e32 v211, 16, v210
	ds_bpermute_b32 v207, v211, v201
	ds_bpermute_b32 v208, v211, v202
	s_waitcnt lgkmcnt(0)
	v_add_f32_e32 v201, v201, v207
	v_add_f32_e32 v202, v202, v208
	v_xor_b32_e32 v211, 32, v210
	ds_bpermute_b32 v207, v211, v201
	ds_bpermute_b32 v208, v211, v202
	s_waitcnt lgkmcnt(0)
	v_add_f32_e32 v201, v201, v207
	v_add_f32_e32 v202, v202, v208
	v_xor_b32_e32 v211, 64, v210
	ds_bpermute_b32 v207, v211, v201
	ds_bpermute_b32 v208, v211, v202
	s_waitcnt lgkmcnt(0)
	v_add_f32_e32 v201, v201, v207
	v_add_f32_e32 v202, v202, v208
	v_xor_b32_e32 v211, 128, v210
	ds_bpermute_b32 v207, v211, v201
	ds_bpermute_b32 v208, v211, v202
	s_waitcnt lgkmcnt(0)
	v_add_f32_e32 v201, v201, v207
	v_add_f32_e32 v202, v202, v208
	v_mov_b32_e32 v212, 0x358637bd
	s_nop 0
	v_fmamk_f32 v213, v201, 0x3a800000, v212
	v_fmamk_f32 v214, v202, 0x3a800000, v212
	v_rsq_f32_e32 v215, v213
	v_rsq_f32_e32 v216, v214
	s_nop 0
	v_mul_f32_e32 v217, v213, v215
	v_mul_f32_e32 v218, v214, v216
	v_fma_f32 v217, -v217, v215, 1.0
	v_fma_f32 v218, -v218, v216, 1.0
	v_mul_f32_e32 v219, 0.5, v215
	v_mul_f32_e32 v220, 0.5, v216
	v_fma_f32 v222, v219, v217, v215
	v_fma_f32 v224, v220, v218, v216
	s_lshl_b32 s100, s98, 11
	s_add_u32 s100, s100, s64
	s_addc_u32 s101, s65, 0
	s_add_u32 s100, s100, 0x1100000
	s_addc_u32 s101, s101, 0
	v_lshrrev_b32_e32 v221, 1, v254
	s_cmp_eq_u32 s32, 1
	s_cbranch_scc0 .Lax_wt
	v_pk_mul_f32 v[226:227], v[232:233], v[222:223] op_sel_hi:[1,0]
	v_pk_mul_f32 v[228:229], v[234:235], v[222:223] op_sel_hi:[1,0]
	v_cvt_pk_bf16_f32 v230, v226, v227
	v_cvt_pk_bf16_f32 v231, v228, v229
	global_store_dwordx2 v221, v[230:231], s[100:101] offset:0
	v_pk_mul_f32 v[226:227], v[236:237], v[222:223] op_sel_hi:[1,0]
	v_pk_mul_f32 v[228:229], v[238:239], v[222:223] op_sel_hi:[1,0]
	v_cvt_pk_bf16_f32 v202, v226, v227
	v_cvt_pk_bf16_f32 v203, v228, v229
	global_store_dwordx2 v221, v[202:203], s[100:101] offset:512
	v_pk_mul_f32 v[226:227], v[240:241], v[222:223] op_sel_hi:[1,0]
	v_pk_mul_f32 v[228:229], v[242:243], v[222:223] op_sel_hi:[1,0]
	v_cvt_pk_bf16_f32 v230, v226, v227
	v_cvt_pk_bf16_f32 v231, v228, v229
	global_store_dwordx2 v221, v[230:231], s[100:101] offset:1024
	v_pk_mul_f32 v[226:227], v[244:245], v[222:223] op_sel_hi:[1,0]
	v_pk_mul_f32 v[228:229], v[246:247], v[222:223] op_sel_hi:[1,0]
	v_cvt_pk_bf16_f32 v202, v226, v227
	v_cvt_pk_bf16_f32 v203, v228, v229
	global_store_dwordx2 v221, v[202:203], s[100:101] offset:1536
	v_pk_mul_f32 v[226:227], v[182:183], v[224:225] op_sel_hi:[1,0]
	v_pk_mul_f32 v[228:229], v[184:185], v[224:225] op_sel_hi:[1,0]
	v_cvt_pk_bf16_f32 v230, v226, v227
	v_cvt_pk_bf16_f32 v231, v228, v229
	global_store_dwordx2 v221, v[230:231], s[100:101] offset:2048
	v_pk_mul_f32 v[226:227], v[250:251], v[224:225] op_sel_hi:[1,0]
	v_pk_mul_f32 v[228:229], v[252:253], v[224:225] op_sel_hi:[1,0]
	v_cvt_pk_bf16_f32 v202, v226, v227
	v_cvt_pk_bf16_f32 v203, v228, v229
	global_store_dwordx2 v221, v[202:203], s[100:101] offset:2560
	v_pk_mul_f32 v[226:227], v[178:179], v[224:225] op_sel_hi:[1,0]
	v_pk_mul_f32 v[228:229], v[180:181], v[224:225] op_sel_hi:[1,0]
	v_cvt_pk_bf16_f32 v230, v226, v227
	v_cvt_pk_bf16_f32 v231, v228, v229
	global_store_dwordx2 v221, v[230:231], s[100:101] offset:3072
	v_pk_mul_f32 v[226:227], v[154:155], v[224:225] op_sel_hi:[1,0]
	v_pk_mul_f32 v[228:229], v[156:157], v[224:225] op_sel_hi:[1,0]
	v_cvt_pk_bf16_f32 v202, v226, v227
	v_cvt_pk_bf16_f32 v203, v228, v229
	global_store_dwordx2 v221, v[202:203], s[100:101] offset:3584
	s_branch .Lax_stdone
; __device__ __forceinline__ unsigned cvt_pk_bf16(float lo, float hi) { const f32x2_t v = {lo, hi}; const bf16x2_t r = __builtin_convertvector(v, bf16x2_t); return __builtin_bit_cast(unsigned, r); }
; __device__ __forceinline__ void p0_proc4(bf16_t* XB, int m0, int NGW, int lane, const f32x4 (&v)[4][4]) {
;     ...
;     for (int u = 0; u < 4; ++u) { const int m = m0 + u * NGW; if (m >= T) break;
;         const float rstd = 1.0f / sqrtf(s[u] * (1.0f / 1024.0f) + NORM_EPS);
;         u32x2* o8 = (u32x2*)(XB + (size_t)m * 1024) + lane;
; #pragma unroll
;         for (int j = 0; j < 4; ++j) { u32x2 w; w.x = cvt_pk_bf16(v[u][j][0] * rstd, v[u][j][1] * rstd); w.y = cvt_pk_bf16(v[u][j][2] * rstd, v[u][j][3] * rstd); o8[64 * j] = w; } }
.Lax_wt:
	v_pk_mul_f32 v[226:227], v[232:233], v[222:223] op_sel_hi:[1,0]
	v_pk_mul_f32 v[228:229], v[234:235], v[222:223] op_sel_hi:[1,0]
	v_cvt_pk_bf16_f32 v230, v226, v227
	v_cvt_pk_bf16_f32 v231, v228, v229
	global_store_dwordx2 v221, v[230:231], s[100:101] offset:0 sc0 sc1
	v_pk_mul_f32 v[226:227], v[236:237], v[222:223] op_sel_hi:[1,0]
	v_pk_mul_f32 v[228:229], v[238:239], v[222:223] op_sel_hi:[1,0]
	v_cvt_pk_bf16_f32 v202, v226, v227
	v_cvt_pk_bf16_f32 v203, v228, v229
	global_store_dwordx2 v221, v[202:203], s[100:101] offset:512 sc0 sc1
	v_pk_mul_f32 v[226:227], v[240:241], v[222:223] op_sel_hi:[1,0]
	v_pk_mul_f32 v[228:229], v[242:243], v[222:223] op_sel_hi:[1,0]
	v_cvt_pk_bf16_f32 v230, v226, v227
	v_cvt_pk_bf16_f32 v231, v228, v229
	global_store_dwordx2 v221, v[230:231], s[100:101] offset:1024 sc0 sc1
	v_pk_mul_f32 v[226:227], v[244:245], v[222:223] op_sel_hi:[1,0]
	v_pk_mul_f32 v[228:229], v[246:247], v[222:223] op_sel_hi:[1,0]
	v_cvt_pk_bf16_f32 v202, v226, v227
	v_cvt_pk_bf16_f32 v203, v228, v229
	global_store_dwordx2 v221, v[202:203], s[100:101] offset:1536 sc0 sc1
	v_pk_mul_f32 v[226:227], v[182:183], v[224:225] op_sel_hi:[1,0]
	v_pk_mul_f32 v[228:229], v[184:185], v[224:225] op_sel_hi:[1,0]
	v_cvt_pk_bf16_f32 v230, v226, v227
	v_cvt_pk_bf16_f32 v231, v228, v229
	global_store_dwordx2 v221, v[230:231], s[100:101] offset:2048 sc0 sc1
	v_pk_mul_f32 v[226:227], v[250:251], v[224:225] op_sel_hi:[1,0]
	v_pk_mul_f32 v[228:229], v[252:253], v[224:225] op_sel_hi:[1,0]
	v_cvt_pk_bf16_f32 v202, v226, v227
	v_cvt_pk_bf16_f32 v203, v228, v229
	global_store_dwordx2 v221, v[202:203], s[100:101] offset:2560 sc0 sc1
	v_pk_mul_f32 v[226:227], v[178:179], v[224:225] op_sel_hi:[1,0]
	v_pk_mul_f32 v[228:229], v[180:181], v[224:225] op_sel_hi:[1,0]
	v_cvt_pk_bf16_f32 v230, v226, v227
	v_cvt_pk_bf16_f32 v231, v228, v229
	global_store_dwordx2 v221, v[230:231], s[100:101] offset:3072 sc0 sc1
	v_pk_mul_f32 v[226:227], v[154:155], v[224:225] op_sel_hi:[1,0]
	v_pk_mul_f32 v[228:229], v[156:157], v[224:225] op_sel_hi:[1,0]
	v_cvt_pk_bf16_f32 v202, v226, v227
	v_cvt_pk_bf16_f32 v203, v228, v229
	global_store_dwordx2 v221, v[202:203], s[100:101] offset:3584 sc0 sc1
.Lax_stdone:
	ds_read_b128 v[178:181], v255
	ds_read_b128 v[154:157], v255 offset:1024
	s_waitcnt lgkmcnt(0)

; #define SEAM(k) do { if (IN(k) && IN((k) + 1)) { XcdBarrier gb_; gb_.bar = (unsigned*)(ws + WS_CTL); gb_.x = xb_xcc_id(); gb_.st = (volatile LAS unsigned*)(lds + LDS_BYTES - 64); xcd_barrier(gb_); } } while (0)
; __device__ __forceinline__ void p0_prologue(const Args& a, LAS unsigned char* lds, int wave, int lane) {
;     ...
;         for (int it = gw; it < NITEMS; it += NGW) {
;             int r = it;
;             if (r < I_IN) { const int kb = r / 168, nb = r % 168; p0_transpose_item(w_in, NIN, 64 * kb, map_col(32 * nb), ng, WIN, 32 * nb, 64 * kb, scr, lane); continue; } r -= I_IN;
;             if (r < I_OA) { const int kb = r / 32, nb = r % 32; p0_transpose_item(w_oa, 1024, 64 * kb, 32 * nb, nullptr, WAB, 32 * nb, 64 * kb, scr, lane); continue; } r -= I_OA;
;             if (r < I_OB) { const int kb = r / 32, nb = r % 32; p0_transpose_item(w_ob, 1024, 64 * kb, 32 * nb, nullptr, WAB, 32 * nb, 512 + 64 * kb, scr, lane); continue; } r -= I_OB;
;             { const int kb = r / 32, nb = r % 32; p0_transpose_item(w_o, 1024, 64 * kb, 32 * nb, nullptr, WO, 32 * nb, 64 * kb, scr, lane); }
; __global__ void __launch_bounds__(512, 2) fwd_kernel(Args a) {
;     ...
;     if (IN(0)) { p0_prologue(a, lds, wave, lane); }
;     SEAM(0);
.Lax_nosig_z:
	s_cmp_lt_u32 s2, 192
	s_cbranch_scc1 .Llate_ret
	s_load_dwordx16 s[76:91], s[74:75], 0x0
	s_load_dwordx2 s[60:61], s[74:75], 0x60
	v_readfirstlane_b32 s3, v190
	s_movk_i32 s32, 0xe7f
	s_lshr_b32 s3, s3, 6
	s_sub_i32 s0, s2, 192
	s_lshl_b32 s0, s0, 3
	s_add_i32 s20, s3, s0
	s_addk_i32 s20, 0xa80
	s_waitcnt lgkmcnt(0)
	s_branch .Llate_entry
.Llate_done:
	s_waitcnt vmcnt(0) lgkmcnt(0)
	s_barrier
	s_cmp_lt_i32 s66, 2
	s_cselect_b64 s[6:7], -1, 0
	s_cmp_gt_i32 s67, 1
	s_cselect_b64 s[0:1], -1, 0
	s_and_b64 s[6:7], s[6:7], s[0:1]
